# v23 plus thin-phase mix2 partial loads hoisted and GEMM phase-start load batches overlapped
# baseline (speedup 1.0000x reference)
.LBB0_235:
	s_lshl_b32 s12, s12, 5
	v_mov_b32_e32 v133, v3
	s_and_b32 s17, s12, 0x60
	s_add_i32 m0, s35, 0x18000
	v_lshl_add_u64 v[6:7], v[6:7], 0, s[66:67]
	v_lshl_add_u64 v[14:15], s[56:57], 0, v[132:133]
	v_mov_b32_e32 v137, v3
	s_lshl_b32 s16, s1, 13
	s_lshl_b32 s33, s17, 7
	global_load_lds_dwordx4 v[6:7], off
	v_lshl_add_u64 v[4:5], v[4:5], 0, s[66:67]
	s_add_i32 m0, s35, 0x1a000
	s_add_i32 s63, s35, 0x8000
	s_add_i32 s64, s35, 0xa000
	v_lshl_add_u64 v[16:17], s[56:57], 0, v[136:137]
	global_load_lds_dwordx4 v[4:5], off
	v_lshl_add_u64 v[4:5], v[14:15], 0, s[66:67]
	s_mov_b32 m0, s63
	s_add_u32 s12, s88, 0x80080
	global_load_lds_dwordx4 v[4:5], off
	v_lshl_add_u64 v[4:5], v[16:17], 0, s[66:67]
	s_mov_b32 m0, s64
	s_addc_u32 s13, s89, 0
	global_load_lds_dwordx4 v[4:5], off
	s_add_i32 m0, s35, 0x1c000
	v_lshl_add_u64 v[4:5], s[12:13], 0, v[134:135]
	global_load_lds_dwordx4 v[4:5], off
	v_lshl_add_u64 v[4:5], s[12:13], 0, v[138:139]
	s_add_i32 m0, s35, 0x1e000
	s_cmpk_lt_u32 s0, 0x100
	global_load_lds_dwordx4 v[4:5], off
	v_lshrrev_b32_e32 v5, 1, v1
	v_and_b32_e32 v5, 24, v5
	v_and_b32_e32 v4, 15, v1
	v_lshlrev_b32_e32 v6, 1, v5
	v_lshlrev_b32_e32 v1, 2, v1
	v_bfe_u32 v140, v0, 2, 4
	v_lshl_or_b32 v140, s1, 6, v140
	v_bfe_u32 v231, v0, 2, 4
	v_and_b32_e32 v230, 3, v0
	v_lshl_or_b32 v231, v230, 4, v231
	v_lshlrev_b32_e32 v231, 2, v231
	v_lshl_or_b32 v4, v4, 6, v6
	v_and_b32_e32 v1, 32, v1
	v_bitop3_b32 v6, v4, s16, v1 bitop3:0xde
	v_bitop3_b32 v1, v4, s33, v1 bitop3:0xde
	v_lshlrev_b32_e32 v4, 15, v2
	v_and_b32_e32 v4, 0xffff0000, v4
	v_lshl_add_u32 v4, v8, 12, v4
	v_and_b32_e32 v2, 1, v2
	v_lshl_or_b32 v2, v2, 6, v4
	v_lshl_add_u32 v146, v9, 1, v2
	v_lshlrev_b32_e32 v2, 15, v10
	v_readlane_b32 s0, v252, 26
	v_and_b32_e32 v2, 0xffff0000, v2
	v_readlane_b32 s1, v252, 27
	s_waitcnt vmcnt(8)
	s_barrier
	s_waitcnt vmcnt(6)
	v_lshl_add_u32 v2, v11, 12, v2
	v_and_b32_e32 v4, 1, v10
	s_mov_b32 s50, s0
	v_readlane_b32 s0, v252, 24
	v_ashrrev_i32_e32 v141, 31, v140
	v_lshl_or_b32 v2, v4, 6, v2
	v_readlane_b32 s1, v252, 25
	s_mov_b32 s55, 32
	s_cselect_b64 s[58:59], -1, 0
	v_and_b32_e32 v142, 3, v0
	v_lshl_or_b32 v142, v142, 3, s17
	v_lshlrev_b64 v[144:145], 10, v[140:141]
	v_mov_b32_e32 v147, v3
	v_lshl_add_u32 v148, v12, 1, v2
	v_mov_b32_e32 v149, v3
	s_mov_b32 s51, 0
	v_add_u32_e32 v141, 0, v6
	s_mov_b32 s54, s0
	s_mov_b64 s[0:1], s[56:57]
	s_mov_b32 s13, 0
	s_barrier
	s_branch .LBB0_238

.LBB0_513:
	v_readlane_b32 s74, v252, 10
	s_add_u32 s0, s84, 0x80080
	v_mov_b32_e32 v133, v3
	v_readlane_b32 s75, v252, 11
	s_addc_u32 s1, s85, 0
	s_add_i32 m0, s17, 0x18000
	v_lshl_add_u64 v[6:7], v[6:7], 0, s[66:67]
	v_lshl_add_u64 v[16:17], s[74:75], 0, v[132:133]
	v_mov_b32_e32 v135, v3
	global_load_lds_dwordx4 v[6:7], off
	v_lshl_add_u64 v[4:5], v[4:5], 0, s[66:67]
	s_add_i32 m0, s17, 0x1a000
	s_add_i32 s62, s17, 0x8000
	v_lshl_add_u64 v[18:19], s[74:75], 0, v[134:135]
	global_load_lds_dwordx4 v[4:5], off
	v_lshl_add_u64 v[4:5], v[16:17], 0, s[66:67]
	s_mov_b32 m0, s62
	s_add_i32 s63, s17, 0xa000
	global_load_lds_dwordx4 v[4:5], off
	v_lshl_add_u64 v[4:5], v[18:19], 0, s[66:67]
	s_mov_b32 m0, s63
	v_lshrrev_b32_e32 v20, 1, v14
	global_load_lds_dwordx4 v[4:5], off
	s_add_i32 m0, s17, 0x1c000
	v_lshl_add_u64 v[4:5], s[0:1], 0, v[2:3]
	global_load_lds_dwordx4 v[4:5], off
	v_lshl_add_u64 v[4:5], s[0:1], 0, v[136:137]
	s_add_i32 m0, s17, 0x1e000
	v_and_b32_e32 v20, 24, v20
	global_load_lds_dwordx4 v[4:5], off
	v_lshlrev_b32_e32 v4, 15, v8
	v_and_b32_e32 v4, 0xffff0000, v4
	v_lshl_add_u32 v4, v9, 12, v4
	v_and_b32_e32 v5, 1, v8
	v_lshl_or_b32 v4, v5, 6, v4
	s_lshl_b32 s23, s23, 5
	v_lshl_add_u32 v138, v10, 1, v4
	v_lshlrev_b32_e32 v4, 15, v11
	v_and_b32_e32 v15, 15, v14
	v_lshlrev_b32_e32 v21, 1, v20
	v_lshlrev_b32_e32 v14, 2, v14
	s_and_b32 s23, s23, 0x60
	v_and_b32_e32 v4, 0xffff0000, v4
	v_bfe_u32 v1, v0, 2, 4
	v_lshl_or_b32 v1, s35, 6, v1
	v_bfe_u32 v231, v0, 2, 4
	v_and_b32_e32 v230, 3, v0
	v_lshl_or_b32 v231, v230, 4, v231
	v_lshlrev_b32_e32 v231, 2, v231
	v_lshl_or_b32 v15, v15, 6, v21
	v_and_b32_e32 v14, 32, v14
	s_lshl_b32 s35, s35, 13
	s_lshl_b32 s50, s23, 7
	s_waitcnt vmcnt(8)
	s_barrier
	s_waitcnt vmcnt(6)
	v_lshl_add_u32 v4, v12, 12, v4
	v_and_b32_e32 v5, 1, v11
	v_bitop3_b32 v142, v15, s50, v14 bitop3:0xde
	v_bitop3_b32 v14, v15, s35, v14 bitop3:0xde
	s_cmpk_lt_u32 s9, 0x100
	v_lshl_or_b32 v4, v5, 6, v4
	v_readlane_b32 s0, v252, 17
	s_mov_b32 s64, 32
	s_cselect_b64 s[58:59], -1, 0
	v_and_b32_e32 v143, 3, v0
	v_lshl_or_b32 v143, v143, 3, s23
	v_mov_b32_e32 v139, v3
	v_lshl_add_u32 v140, v13, 1, v4
	v_mov_b32_e32 v141, v3
	s_mov_b64 s[86:87], -1
	s_mov_b32 s50, 0
	v_add_u32_e32 v144, 0, v14
	s_mov_b32 s51, s0
	s_barrier
	v_readlane_b32 s1, v252, 18
	s_branch .LBB0_516

.LBB0_613:
	s_add_i32 s36, s23, s9
	s_cmpk_lt_i32 s36, 0x2000
	s_cbranch_scc1 .Lmix2_p4a
	s_add_i32 s64, s36, 0xffffe000
	s_lshl_b64 s[12:13], s[64:65], 12
	v_lshl_add_u64 v[120:121], v[42:43], 0, s[12:13]
	global_load_dwordx4 v[104:107], v[120:121], off
	global_load_dwordx4 v[108:111], v[120:121], off offset:1024
	global_load_dwordx4 v[112:115], v[120:121], off offset:2048
	global_load_dwordx4 v[116:119], v[120:121], off offset:3072
.Lmix2_p4a:
	s_cmpk_lt_i32 s36, 0x2000
	s_cselect_b64 s[68:69], -1, 0
	s_cmpk_gt_i32 s36, 0x1fff
	s_cselect_b64 s[72:73], -1, 0
	s_and_b64 vcc, exec, s[0:1]
	s_cbranch_vccz .LBB0_615
	s_ashr_i32 s37, s36, 31
	s_lshl_b64 s[12:13], s[36:37], 12
	v_lshl_add_u64 v[16:17], v[40:41], 0, s[12:13]
	global_load_dwordx4 v[4:7], v[16:17], off
	global_load_dwordx4 v[8:11], v[16:17], off offset:1024
	global_load_dwordx4 v[12:15], v[16:17], off offset:2048
	global_load_dwordx4 v[46:49], v[16:17], off offset:3072
	s_waitcnt vmcnt(3)
	v_lshlrev_b32_e32 v32, 16, v4
	v_and_b32_e32 v33, 0xffff0000, v4
	v_lshlrev_b32_e32 v34, 16, v5
	v_and_b32_e32 v35, 0xffff0000, v5
	v_lshlrev_b32_e32 v28, 16, v6
	v_and_b32_e32 v29, 0xffff0000, v6
	v_lshlrev_b32_e32 v30, 16, v7
	v_and_b32_e32 v31, 0xffff0000, v7
	s_waitcnt vmcnt(2)
	v_lshlrev_b32_e32 v24, 16, v8
	v_and_b32_e32 v25, 0xffff0000, v8
	v_lshlrev_b32_e32 v26, 16, v9
	v_and_b32_e32 v27, 0xffff0000, v9
	v_lshlrev_b32_e32 v20, 16, v10
	v_and_b32_e32 v21, 0xffff0000, v10
	v_lshlrev_b32_e32 v22, 16, v11
	v_and_b32_e32 v23, 0xffff0000, v11
	s_waitcnt vmcnt(1)
	v_lshlrev_b32_e32 v16, 16, v12
	v_and_b32_e32 v17, 0xffff0000, v12
	v_lshlrev_b32_e32 v18, 16, v13
	v_and_b32_e32 v19, 0xffff0000, v13
	v_lshlrev_b32_e32 v12, 16, v14
	v_and_b32_e32 v13, 0xffff0000, v14
	v_lshlrev_b32_e32 v14, 16, v15
	v_and_b32_e32 v15, 0xffff0000, v15
	s_waitcnt vmcnt(0)
	v_lshlrev_b32_e32 v8, 16, v46
	v_and_b32_e32 v9, 0xffff0000, v46
	v_lshlrev_b32_e32 v10, 16, v47
	v_and_b32_e32 v11, 0xffff0000, v47
	v_lshlrev_b32_e32 v4, 16, v48
	v_and_b32_e32 v5, 0xffff0000, v48
	v_lshlrev_b32_e32 v6, 16, v49
	v_and_b32_e32 v7, 0xffff0000, v49
	s_cbranch_execz .LBB0_616
	s_branch .LBB0_621

.LBB0_621:
	s_lshl_b64 s[12:13], s[36:37], 12
	v_lshl_add_u64 v[58:59], v[38:39], 0, s[12:13]
	global_load_dwordx4 v[46:49], v[58:59], off
	global_load_dwordx4 v[50:53], v[58:59], off offset:1024
	global_load_dwordx4 v[54:57], v[58:59], off offset:2048
	global_load_dwordx4 v[78:81], v[58:59], off offset:3072
	s_cmpk_lt_i32 s36, 0x2000
	s_waitcnt vmcnt(3)
	v_lshlrev_b32_e32 v74, 16, v46
	v_and_b32_e32 v75, 0xffff0000, v46
	v_lshlrev_b32_e32 v76, 16, v47
	v_and_b32_e32 v77, 0xffff0000, v47
	v_lshlrev_b32_e32 v70, 16, v48
	v_and_b32_e32 v71, 0xffff0000, v48
	v_lshlrev_b32_e32 v72, 16, v49
	v_and_b32_e32 v73, 0xffff0000, v49
	s_waitcnt vmcnt(2)
	v_lshlrev_b32_e32 v66, 16, v50
	v_and_b32_e32 v67, 0xffff0000, v50
	v_lshlrev_b32_e32 v68, 16, v51
	v_and_b32_e32 v69, 0xffff0000, v51
	v_lshlrev_b32_e32 v62, 16, v52
	v_and_b32_e32 v63, 0xffff0000, v52
	v_lshlrev_b32_e32 v64, 16, v53
	v_and_b32_e32 v65, 0xffff0000, v53
	s_waitcnt vmcnt(1)
	v_lshlrev_b32_e32 v60, 16, v54
	v_and_b32_e32 v61, 0xffff0000, v54
	v_lshlrev_b32_e32 v58, 16, v55
	v_and_b32_e32 v59, 0xffff0000, v55
	v_lshlrev_b32_e32 v54, 16, v56
	v_and_b32_e32 v55, 0xffff0000, v56
	v_lshlrev_b32_e32 v56, 16, v57
	v_and_b32_e32 v57, 0xffff0000, v57
	s_waitcnt vmcnt(0)
	v_lshlrev_b32_e32 v50, 16, v78
	v_and_b32_e32 v51, 0xffff0000, v78
	v_lshlrev_b32_e32 v52, 16, v79
	v_and_b32_e32 v53, 0xffff0000, v79
	v_lshlrev_b32_e32 v48, 16, v80
	v_and_b32_e32 v49, 0xffff0000, v80
	v_lshlrev_b32_e32 v46, 16, v81
	v_and_b32_e32 v47, 0xffff0000, v81
	s_cbranch_scc1 .LBB0_623
	s_add_i32 s64, s36, 0xffffe000
	s_lshl_b64 s[12:13], s[64:65], 12
	v_lshl_add_u64 v[82:83], v[42:43], 0, s[12:13]
	v_mov_b32_e32 v78, v104
	v_mov_b32_e32 v79, v105
	v_mov_b32_e32 v80, v106
	v_mov_b32_e32 v81, v107
	v_lshlrev_b32_e32 v84, 16, v78
	v_and_b32_e32 v85, 0xffff0000, v78
	v_lshlrev_b32_e32 v78, 16, v79
	v_and_b32_e32 v79, 0xffff0000, v79
	v_pk_add_f32 v[76:77], v[76:77], v[78:79]
	v_lshlrev_b32_e32 v78, 16, v80
	v_and_b32_e32 v79, 0xffff0000, v80
	v_lshlrev_b32_e32 v80, 16, v81
	v_and_b32_e32 v81, 0xffff0000, v81
	v_pk_add_f32 v[72:73], v[72:73], v[80:81]
	v_pk_add_f32 v[70:71], v[70:71], v[78:79]
	v_mov_b32_e32 v78, v108
	v_mov_b32_e32 v79, v109
	v_mov_b32_e32 v80, v110
	v_mov_b32_e32 v81, v111
	v_pk_add_f32 v[74:75], v[74:75], v[84:85]
	v_lshlrev_b32_e32 v84, 16, v78
	v_and_b32_e32 v85, 0xffff0000, v78
	v_lshlrev_b32_e32 v78, 16, v79
	v_and_b32_e32 v79, 0xffff0000, v79
	v_pk_add_f32 v[68:69], v[68:69], v[78:79]
	v_lshlrev_b32_e32 v78, 16, v80
	v_and_b32_e32 v79, 0xffff0000, v80
	v_lshlrev_b32_e32 v80, 16, v81
	v_and_b32_e32 v81, 0xffff0000, v81
	v_pk_add_f32 v[64:65], v[64:65], v[80:81]
	v_pk_add_f32 v[62:63], v[62:63], v[78:79]
	v_mov_b32_e32 v78, v112
	v_mov_b32_e32 v79, v113
	v_mov_b32_e32 v80, v114
	v_mov_b32_e32 v81, v115
	v_pk_add_f32 v[66:67], v[66:67], v[84:85]
	v_lshlrev_b32_e32 v84, 16, v78
	v_and_b32_e32 v85, 0xffff0000, v78
	v_lshlrev_b32_e32 v78, 16, v79
	v_and_b32_e32 v79, 0xffff0000, v79
	v_pk_add_f32 v[58:59], v[58:59], v[78:79]
	v_lshlrev_b32_e32 v78, 16, v80
	v_and_b32_e32 v79, 0xffff0000, v80
	v_lshlrev_b32_e32 v80, 16, v81
	v_and_b32_e32 v81, 0xffff0000, v81
	v_pk_add_f32 v[56:57], v[56:57], v[80:81]
	v_pk_add_f32 v[54:55], v[54:55], v[78:79]
	v_mov_b32_e32 v78, v116
	v_mov_b32_e32 v79, v117
	v_mov_b32_e32 v80, v118
	v_mov_b32_e32 v81, v119
	v_pk_add_f32 v[60:61], v[60:61], v[84:85]
	v_lshlrev_b32_e32 v82, 16, v78
	v_and_b32_e32 v83, 0xffff0000, v78
	v_lshlrev_b32_e32 v78, 16, v79
	v_and_b32_e32 v79, 0xffff0000, v79
	v_pk_add_f32 v[52:53], v[52:53], v[78:79]
	v_lshlrev_b32_e32 v78, 16, v80
	v_and_b32_e32 v79, 0xffff0000, v80
	v_lshlrev_b32_e32 v80, 16, v81
	v_and_b32_e32 v81, 0xffff0000, v81
	v_pk_add_f32 v[50:51], v[50:51], v[82:83]
	v_pk_add_f32 v[46:47], v[46:47], v[80:81]
	v_pk_add_f32 v[48:49], v[48:49], v[78:79]
.LBB0_623:
	v_mov_b32_e32 v80, v71
	v_mov_b32_e32 v81, v75
	v_mov_b32_e32 v78, v70
	v_mov_b32_e32 v79, v74
	v_pk_mul_f32 v[80:81], v[80:81], v[80:81]
	v_mov_b32_e32 v82, v73
	v_mov_b32_e32 v83, v77
	v_pk_fma_f32 v[78:79], v[78:79], v[78:79], v[80:81]
	v_mov_b32_e32 v80, v72
	v_mov_b32_e32 v81, v76
	v_pk_mul_f32 v[82:83], v[82:83], v[82:83]
	v_mul_f32_e32 v2, v62, v62
	v_pk_fma_f32 v[80:81], v[80:81], v[80:81], v[82:83]
	v_pk_mul_f32 v[82:83], v[66:67], v[66:67]
	v_pk_add_f32 v[78:79], v[78:79], v[80:81]
	v_pk_mul_f32 v[80:81], v[68:69], v[68:69]
	v_pk_add_f32 v[78:79], v[78:79], v[78:79] op_sel_hi:[0,1]
	v_pk_mov_b32 v[84:85], v[82:83], v[80:81] op_sel:[1,0]
	v_mov_b32_e32 v83, v81
	v_pk_add_f32 v[80:81], v[84:85], v[82:83]
	v_pk_fma_f32 v[82:83], v[62:63], v[62:63], v[2:3] op_sel_hi:[1,1,0]
	v_mul_f32_e32 v2, v64, v64
	v_pk_add_f32 v[80:81], v[80:81], v[80:81] op_sel_hi:[0,1]
	v_pk_fma_f32 v[84:85], v[64:65], v[64:65], v[2:3] op_sel_hi:[1,1,0]
	v_mul_f32_e32 v82, v60, v60
	v_mul_f32_e32 v84, v61, v61
	v_mul_f32_e32 v80, v58, v58
	v_mul_f32_e32 v78, v59, v59
	v_pk_add_f32 v[82:83], v[82:83], v[84:85]
	v_pk_add_f32 v[78:79], v[80:81], v[78:79]
	v_pk_mul_f32 v[80:81], v[56:57], v[56:57]
	v_pk_add_f32 v[78:79], v[82:83], v[78:79]
	v_pk_mul_f32 v[82:83], v[54:55], v[54:55]
	v_mul_f32_e32 v2, v50, v50
	v_pk_mov_b32 v[84:85], v[82:83], v[80:81] op_sel:[1,0]
	v_mov_b32_e32 v83, v81
	v_pk_add_f32 v[80:81], v[84:85], v[82:83]
	v_pk_fma_f32 v[82:83], v[50:51], v[50:51], v[2:3] op_sel_hi:[1,1,0]
	v_mul_f32_e32 v2, v52, v52
	v_pk_add_f32 v[78:79], v[78:79], v[78:79] op_sel_hi:[0,1]
	v_pk_add_f32 v[80:81], v[80:81], v[80:81] op_sel_hi:[0,1]
	v_pk_fma_f32 v[84:85], v[52:53], v[52:53], v[2:3] op_sel_hi:[1,1,0]
	v_mul_f32_e32 v82, v48, v48
	v_mul_f32_e32 v84, v49, v49
	v_mul_f32_e32 v80, v46, v46
	v_mul_f32_e32 v78, v47, v47
	v_pk_add_f32 v[82:83], v[82:83], v[84:85]
	v_pk_add_f32 v[78:79], v[80:81], v[78:79]
	v_mov_b32_e32 v37, v3
	v_pk_add_f32 v[78:79], v[82:83], v[78:79]
	s_lshl_b64 s[72:73], s[36:37], 11
	v_add_f32_e32 v2, v78, v79
	s_cmpk_lt_i32 s36, 0x2800
	s_cselect_b32 s16, 0x800, s41
	v_add_f32_dpp v2, v2, v2 quad_perm:[1,0,3,2] row_mask:0xf bank_mask:0xf bound_ctrl:1
	s_and_b64 s[12:13], s[68:69], exec
	s_cselect_b32 s12, 0, s16
	v_add_f32_dpp v2, v2, v2 quad_perm:[2,3,0,1] row_mask:0xf bank_mask:0xf bound_ctrl:1
	s_lshl_b32 s12, s12, 2
	s_lshl_b64 s[68:69], s[72:73], 1
	v_add_f32_dpp v2, v2, v2 row_ror:4 row_mask:0xf bank_mask:0xf bound_ctrl:1
	s_add_i32 s72, s36, 1
	s_cmpk_lt_i32 s72, 0x2000
	v_add_f32_dpp v2, v2, v2 row_ror:8 row_mask:0xf bank_mask:0xf bound_ctrl:1
	s_nop 1
	v_mov_b32_dpp v37, v2 row_bcast:15 row_mask:0xa bank_mask:0xf
	v_add_f32_e32 v2, v2, v37
	v_mov_b32_e32 v37, v3
	s_nop 1
	v_mov_b32_dpp v37, v2 row_bcast:31 row_mask:0xc bank_mask:0xf
	v_add_f32_e32 v2, v2, v37
	v_add_u32_e32 v37, s12, v1
	v_readlane_b32 s13, v2, 63
	ds_read_b128 v[78:81], v37
	ds_read_b128 v[82:85], v37 offset:16
	v_fma_f32 v2, s13, v245, v233
	v_rsq_f32_e32 v2, v2
	s_nop 0
	v_pk_mul_f32 v[74:75], v[2:3], v[74:75] op_sel_hi:[0,1]
	s_waitcnt lgkmcnt(1)
	v_pk_fma_f32 v[74:75], v[78:79], v[74:75], v[32:33]
	v_pk_mul_f32 v[32:33], v[2:3], v[72:73] op_sel_hi:[0,1]
	v_pk_mul_f32 v[76:77], v[2:3], v[76:77] op_sel_hi:[0,1]
	v_pk_mul_f32 v[70:71], v[2:3], v[70:71] op_sel_hi:[0,1]
	s_waitcnt lgkmcnt(0)
	v_pk_fma_f32 v[72:73], v[84:85], v[32:33], v[30:31]
	ds_read_b128 v[30:33], v37 offset:2048
	v_pk_fma_f32 v[34:35], v[80:81], v[76:77], v[34:35]
	v_pk_fma_f32 v[70:71], v[82:83], v[70:71], v[28:29]
	v_pk_mul_f32 v[28:29], v[2:3], v[66:67] op_sel_hi:[0,1]
	v_pk_mul_f32 v[76:77], v[2:3], v[68:69] op_sel_hi:[0,1]
	ds_read_b128 v[66:69], v37 offset:2064
	s_waitcnt lgkmcnt(1)
	v_pk_fma_f32 v[30:31], v[30:31], v[28:29], v[24:25]
	v_pk_mul_f32 v[24:25], v[2:3], v[64:65] op_sel_hi:[0,1]
	v_pk_fma_f32 v[32:33], v[32:33], v[76:77], v[26:27]
	v_pk_mul_f32 v[26:27], v[2:3], v[62:63] op_sel_hi:[0,1]
	s_waitcnt lgkmcnt(0)
	v_pk_fma_f32 v[62:63], v[68:69], v[24:25], v[22:23]
	ds_read_b128 v[22:25], v37 offset:4096
	v_pk_fma_f32 v[64:65], v[66:67], v[26:27], v[20:21]
	ds_read_b128 v[26:29], v37 offset:4112
	v_pk_mul_f32 v[20:21], v[2:3], v[60:61] op_sel_hi:[0,1]
	v_pk_mul_f32 v[58:59], v[2:3], v[58:59] op_sel_hi:[0,1]
	s_waitcnt lgkmcnt(1)
	v_pk_fma_f32 v[22:23], v[22:23], v[20:21], v[16:17]
	v_pk_mul_f32 v[16:17], v[2:3], v[56:57] op_sel_hi:[0,1]
	v_pk_fma_f32 v[24:25], v[24:25], v[58:59], v[18:19]
	v_pk_mul_f32 v[18:19], v[2:3], v[54:55] op_sel_hi:[0,1]
	s_waitcnt lgkmcnt(0)
	v_pk_fma_f32 v[28:29], v[28:29], v[16:17], v[14:15]
	ds_read_b128 v[14:17], v37 offset:6144
	v_pk_fma_f32 v[26:27], v[26:27], v[18:19], v[12:13]
	ds_read_b128 v[18:21], v37 offset:6160
	v_pk_mul_f32 v[12:13], v[2:3], v[50:51] op_sel_hi:[0,1]
	v_pk_mul_f32 v[50:51], v[2:3], v[52:53] op_sel_hi:[0,1]
	s_waitcnt lgkmcnt(1)
	v_pk_fma_f32 v[50:51], v[50:51], v[16:17], v[10:11]
	v_pk_fma_f32 v[52:53], v[12:13], v[14:15], v[8:9]
	v_pk_mul_f32 v[8:9], v[2:3], v[48:49] op_sel_hi:[0,1]
	v_pk_mul_f32 v[10:11], v[2:3], v[46:47] op_sel_hi:[0,1]
	s_waitcnt lgkmcnt(0)
	v_pk_fma_f32 v[20:21], v[10:11], v[20:21], v[6:7]
	v_pk_fma_f32 v[46:47], v[8:9], v[18:19], v[4:5]
	v_lshl_add_u64 v[8:9], v[40:41], 0, s[68:69]
	v_cvt_pk_bf16_f32 v4, v74, v75
	v_cvt_pk_bf16_f32 v5, v34, v35
	v_cvt_pk_bf16_f32 v6, v70, v71
	v_cvt_pk_bf16_f32 v7, v72, v73
	global_store_dwordx4 v[8:9], v[4:7], off
	v_mul_f32_e32 v2, v64, v64
	s_nop 0
	v_cvt_pk_bf16_f32 v4, v30, v31
	v_cvt_pk_bf16_f32 v5, v32, v33
	v_cvt_pk_bf16_f32 v6, v64, v65
	v_cvt_pk_bf16_f32 v7, v62, v63
	global_store_dwordx4 v[8:9], v[4:7], off offset:1024
	s_nop 1
	v_cvt_pk_bf16_f32 v4, v22, v23
	v_cvt_pk_bf16_f32 v5, v24, v25
	v_cvt_pk_bf16_f32 v6, v26, v27
	v_cvt_pk_bf16_f32 v7, v28, v29
	global_store_dwordx4 v[8:9], v[4:7], off offset:2048
	s_nop 1
	v_cvt_pk_bf16_f32 v4, v52, v53
	v_cvt_pk_bf16_f32 v5, v50, v51
	v_cvt_pk_bf16_f32 v6, v46, v47
	v_cvt_pk_bf16_f32 v7, v20, v21
	global_store_dwordx4 v[8:9], v[4:7], off offset:3072
	v_mov_b32_e32 v8, v35
	v_mov_b32_e32 v9, v73
	v_mov_b32_e32 v6, v75
	v_mov_b32_e32 v7, v71
	v_mov_b32_e32 v4, v74
	v_mov_b32_e32 v5, v70
	v_pk_mul_f32 v[6:7], v[6:7], v[6:7]
	v_pk_mul_f32 v[8:9], v[8:9], v[8:9]
	v_pk_fma_f32 v[4:5], v[4:5], v[4:5], v[6:7]
	v_mov_b32_e32 v6, v34
	v_mov_b32_e32 v7, v72
	v_pk_fma_f32 v[6:7], v[6:7], v[6:7], v[8:9]
	v_pk_mul_f32 v[8:9], v[30:31], v[30:31]
	v_pk_add_f32 v[4:5], v[4:5], v[6:7]
	v_pk_mul_f32 v[6:7], v[32:33], v[32:33]
	v_pk_add_f32 v[4:5], v[4:5], v[4:5] op_sel_hi:[0,1]
	v_pk_mov_b32 v[10:11], v[8:9], v[6:7] op_sel:[1,0]
	v_mov_b32_e32 v9, v7
	v_pk_add_f32 v[6:7], v[10:11], v[8:9]
	v_pk_fma_f32 v[8:9], v[64:65], v[64:65], v[2:3] op_sel_hi:[1,1,0]
	v_mul_f32_e32 v2, v62, v62
	v_pk_add_f32 v[6:7], v[6:7], v[6:7] op_sel_hi:[0,1]
	v_pk_fma_f32 v[10:11], v[62:63], v[62:63], v[2:3] op_sel_hi:[1,1,0]
	v_mul_f32_e32 v8, v22, v22
	v_mul_f32_e32 v10, v23, v23
	v_mul_f32_e32 v6, v24, v24
	v_mul_f32_e32 v4, v25, v25
	v_pk_add_f32 v[8:9], v[8:9], v[10:11]
	v_pk_add_f32 v[4:5], v[6:7], v[4:5]
	v_pk_mul_f32 v[6:7], v[28:29], v[28:29]
	v_pk_add_f32 v[4:5], v[8:9], v[4:5]
	v_pk_mul_f32 v[8:9], v[26:27], v[26:27]
	v_mul_f32_e32 v2, v52, v52
	v_pk_mov_b32 v[10:11], v[8:9], v[6:7] op_sel:[1,0]
	v_mov_b32_e32 v9, v7
	v_pk_add_f32 v[6:7], v[10:11], v[8:9]
	v_pk_fma_f32 v[8:9], v[52:53], v[52:53], v[2:3] op_sel_hi:[1,1,0]
	v_mul_f32_e32 v2, v50, v50
	v_pk_add_f32 v[4:5], v[4:5], v[4:5] op_sel_hi:[0,1]
	v_pk_add_f32 v[6:7], v[6:7], v[6:7] op_sel_hi:[0,1]
	v_pk_fma_f32 v[10:11], v[50:51], v[50:51], v[2:3] op_sel_hi:[1,1,0]
	v_mul_f32_e32 v8, v46, v46
	v_mul_f32_e32 v10, v47, v47
	v_mul_f32_e32 v6, v20, v20
	v_mul_f32_e32 v4, v21, v21
	v_pk_add_f32 v[8:9], v[8:9], v[10:11]
	v_pk_add_f32 v[4:5], v[6:7], v[4:5]
	s_nop 0
	v_pk_add_f32 v[4:5], v[8:9], v[4:5]
	s_nop 0
	v_add_f32_e32 v2, v4, v5
	v_mov_b32_e32 v4, v3
	s_nop 0
	v_add_f32_dpp v2, v2, v2 quad_perm:[1,0,3,2] row_mask:0xf bank_mask:0xf bound_ctrl:1
	s_nop 1
	v_add_f32_dpp v2, v2, v2 quad_perm:[2,3,0,1] row_mask:0xf bank_mask:0xf bound_ctrl:1
	s_nop 1
	v_add_f32_dpp v2, v2, v2 row_ror:4 row_mask:0xf bank_mask:0xf bound_ctrl:1
	s_nop 1
	v_add_f32_dpp v2, v2, v2 row_ror:8 row_mask:0xf bank_mask:0xf bound_ctrl:1
	s_nop 1
	v_mov_b32_dpp v4, v2 row_bcast:15 row_mask:0xa bank_mask:0xf
	v_add_f32_e32 v2, v2, v4
	v_mov_b32_e32 v4, v3
	s_nop 1
	v_mov_b32_dpp v4, v2 row_bcast:31 row_mask:0xc bank_mask:0xf
	v_add_f32_e32 v2, v2, v4
	ds_read_b128 v[4:7], v37 offset:49152
	ds_read_b128 v[8:11], v37 offset:24576
	ds_read_b128 v[12:15], v37 offset:24592
	ds_read_b128 v[16:19], v37 offset:49168
	v_readlane_b32 s12, v2, 63
	s_nop 1
	v_fma_f32 v2, s12, v245, v233
	v_rsq_f32_e32 v2, v2
	s_nop 0
	v_pk_mul_f32 v[48:49], v[74:75], v[2:3] op_sel_hi:[1,0]
	v_pk_mul_f32 v[34:35], v[34:35], v[2:3] op_sel_hi:[1,0]
	s_waitcnt lgkmcnt(2)
	v_pk_fma_f32 v[4:5], v[8:9], v[48:49], v[4:5]
	v_pk_fma_f32 v[6:7], v[10:11], v[34:35], v[6:7]
	v_pk_mul_f32 v[8:9], v[70:71], v[2:3] op_sel_hi:[1,0]
	v_pk_mul_f32 v[10:11], v[72:73], v[2:3] op_sel_hi:[1,0]
	s_waitcnt lgkmcnt(0)
	v_pk_fma_f32 v[8:9], v[12:13], v[8:9], v[16:17]
	v_pk_fma_f32 v[10:11], v[14:15], v[10:11], v[18:19]
	v_cvt_pk_bf16_f32 v4, v4, v5
	v_cvt_pk_bf16_f32 v5, v6, v7
	v_cvt_pk_bf16_f32 v6, v8, v9
	v_cvt_pk_bf16_f32 v7, v10, v11
	v_lshl_add_u64 v[34:35], v[44:45], 0, s[68:69]
	global_store_dwordx4 v[34:35], v[4:7], off
	ds_read_b128 v[4:7], v37 offset:51200
	ds_read_b128 v[8:11], v37 offset:26624
	ds_read_b128 v[12:15], v37 offset:26640
	ds_read_b128 v[16:19], v37 offset:51216
	v_pk_mul_f32 v[30:31], v[30:31], v[2:3] op_sel_hi:[1,0]
	v_pk_mul_f32 v[32:33], v[32:33], v[2:3] op_sel_hi:[1,0]
	s_waitcnt lgkmcnt(2)
	v_pk_fma_f32 v[4:5], v[30:31], v[8:9], v[4:5]
	v_pk_fma_f32 v[6:7], v[32:33], v[10:11], v[6:7]
	v_pk_mul_f32 v[8:9], v[64:65], v[2:3] op_sel_hi:[1,0]
	v_pk_mul_f32 v[10:11], v[62:63], v[2:3] op_sel_hi:[1,0]
	s_waitcnt lgkmcnt(0)
	v_pk_fma_f32 v[8:9], v[8:9], v[12:13], v[16:17]
	v_pk_fma_f32 v[10:11], v[10:11], v[14:15], v[18:19]
	v_cvt_pk_bf16_f32 v4, v4, v5
	v_cvt_pk_bf16_f32 v5, v6, v7
	v_cvt_pk_bf16_f32 v6, v8, v9
	v_cvt_pk_bf16_f32 v7, v10, v11
	global_store_dwordx4 v[34:35], v[4:7], off offset:1024
	ds_read_b128 v[4:7], v37 offset:53248
	ds_read_b128 v[8:11], v37 offset:28672
	ds_read_b128 v[12:15], v37 offset:28688
	ds_read_b128 v[16:19], v37 offset:53264
	v_pk_mul_f32 v[22:23], v[22:23], v[2:3] op_sel_hi:[1,0]
	v_pk_mul_f32 v[24:25], v[24:25], v[2:3] op_sel_hi:[1,0]
	s_waitcnt lgkmcnt(2)
	v_pk_fma_f32 v[4:5], v[22:23], v[8:9], v[4:5]
	v_pk_fma_f32 v[6:7], v[24:25], v[10:11], v[6:7]
	v_pk_mul_f32 v[8:9], v[26:27], v[2:3] op_sel_hi:[1,0]
	v_pk_mul_f32 v[10:11], v[28:29], v[2:3] op_sel_hi:[1,0]
	s_waitcnt lgkmcnt(0)
	v_pk_fma_f32 v[8:9], v[8:9], v[12:13], v[16:17]
	v_pk_fma_f32 v[10:11], v[10:11], v[14:15], v[18:19]
	v_cvt_pk_bf16_f32 v4, v4, v5
	v_cvt_pk_bf16_f32 v5, v6, v7
	v_cvt_pk_bf16_f32 v6, v8, v9
	v_cvt_pk_bf16_f32 v7, v10, v11
	global_store_dwordx4 v[34:35], v[4:7], off offset:2048
	ds_read_b128 v[4:7], v37 offset:55296
	ds_read_b128 v[8:11], v37 offset:30720
	ds_read_b128 v[12:15], v37 offset:30736
	ds_read_b128 v[16:19], v37 offset:55312
	v_pk_mul_f32 v[22:23], v[52:53], v[2:3] op_sel_hi:[1,0]
	v_pk_mul_f32 v[24:25], v[50:51], v[2:3] op_sel_hi:[1,0]
	s_waitcnt lgkmcnt(2)
	v_pk_fma_f32 v[4:5], v[22:23], v[8:9], v[4:5]
	v_pk_fma_f32 v[6:7], v[24:25], v[10:11], v[6:7]
	v_pk_mul_f32 v[8:9], v[46:47], v[2:3] op_sel_hi:[1,0]
	v_pk_mul_f32 v[10:11], v[20:21], v[2:3] op_sel_hi:[1,0]
	s_waitcnt lgkmcnt(0)
	v_pk_fma_f32 v[8:9], v[8:9], v[12:13], v[16:17]
	v_pk_fma_f32 v[10:11], v[10:11], v[14:15], v[18:19]
	s_cselect_b64 s[68:69], -1, 0
	s_cmpk_gt_i32 s72, 0x1fff
	v_cvt_pk_bf16_f32 v4, v4, v5
	v_cvt_pk_bf16_f32 v5, v6, v7
	v_cvt_pk_bf16_f32 v6, v8, v9
	v_cvt_pk_bf16_f32 v7, v10, v11
	s_cselect_b64 s[74:75], -1, 0
	s_andn2_b64 vcc, exec, s[0:1]
	global_store_dwordx4 v[34:35], v[4:7], off offset:3072
	s_cmpk_lt_i32 s72, 0x2000
	s_cbranch_scc1 .Lmix2_p4b
	s_add_i32 s64, s72, 0xffffe000
	s_lshl_b64 s[12:13], s[64:65], 12
	v_lshl_add_u64 v[120:121], v[42:43], 0, s[12:13]
	global_load_dwordx4 v[104:107], v[120:121], off
	global_load_dwordx4 v[108:111], v[120:121], off offset:1024
	global_load_dwordx4 v[112:115], v[120:121], off offset:2048
	global_load_dwordx4 v[116:119], v[120:121], off offset:3072
.Lmix2_p4b:
	s_cbranch_vccnz .LBB0_625
	s_ashr_i32 s73, s72, 31
	s_lshl_b64 s[12:13], s[72:73], 12
	v_lshl_add_u64 v[16:17], v[40:41], 0, s[12:13]
	global_load_dwordx4 v[4:7], v[16:17], off
	global_load_dwordx4 v[8:11], v[16:17], off offset:1024
	global_load_dwordx4 v[12:15], v[16:17], off offset:2048
	global_load_dwordx4 v[46:49], v[16:17], off offset:3072
	s_waitcnt vmcnt(3)
	v_lshlrev_b32_e32 v32, 16, v4
	v_and_b32_e32 v33, 0xffff0000, v4
	v_lshlrev_b32_e32 v34, 16, v5
	v_and_b32_e32 v35, 0xffff0000, v5
	v_lshlrev_b32_e32 v28, 16, v6
	v_and_b32_e32 v29, 0xffff0000, v6
	v_lshlrev_b32_e32 v30, 16, v7
	v_and_b32_e32 v31, 0xffff0000, v7
	s_waitcnt vmcnt(2)
	v_lshlrev_b32_e32 v24, 16, v8
	v_and_b32_e32 v25, 0xffff0000, v8
	v_lshlrev_b32_e32 v26, 16, v9
	v_and_b32_e32 v27, 0xffff0000, v9
	v_lshlrev_b32_e32 v20, 16, v10
	v_and_b32_e32 v21, 0xffff0000, v10
	v_lshlrev_b32_e32 v22, 16, v11
	v_and_b32_e32 v23, 0xffff0000, v11
	s_waitcnt vmcnt(1)
	v_lshlrev_b32_e32 v16, 16, v12
	v_and_b32_e32 v17, 0xffff0000, v12
	v_lshlrev_b32_e32 v18, 16, v13
	v_and_b32_e32 v19, 0xffff0000, v13
	v_lshlrev_b32_e32 v12, 16, v14
	v_and_b32_e32 v13, 0xffff0000, v14
	v_lshlrev_b32_e32 v14, 16, v15
	v_and_b32_e32 v15, 0xffff0000, v15
	s_waitcnt vmcnt(0)
	v_lshlrev_b32_e32 v8, 16, v46
	v_and_b32_e32 v9, 0xffff0000, v46
	v_lshlrev_b32_e32 v10, 16, v47
	v_and_b32_e32 v11, 0xffff0000, v47
	v_lshlrev_b32_e32 v4, 16, v48
	v_and_b32_e32 v5, 0xffff0000, v48
	v_lshlrev_b32_e32 v6, 16, v49
	v_and_b32_e32 v7, 0xffff0000, v49
	s_cbranch_execz .LBB0_626
	s_branch .LBB0_631

.LBB0_631:
	s_lshl_b64 s[12:13], s[72:73], 12
	v_lshl_add_u64 v[58:59], v[38:39], 0, s[12:13]
	global_load_dwordx4 v[46:49], v[58:59], off
	global_load_dwordx4 v[50:53], v[58:59], off offset:1024
	global_load_dwordx4 v[54:57], v[58:59], off offset:2048
	global_load_dwordx4 v[78:81], v[58:59], off offset:3072
	s_cmpk_lt_i32 s36, 0x1fff
	s_waitcnt vmcnt(3)
	v_lshlrev_b32_e32 v74, 16, v46
	v_and_b32_e32 v75, 0xffff0000, v46
	v_lshlrev_b32_e32 v76, 16, v47
	v_and_b32_e32 v77, 0xffff0000, v47
	v_lshlrev_b32_e32 v70, 16, v48
	v_and_b32_e32 v71, 0xffff0000, v48
	v_lshlrev_b32_e32 v72, 16, v49
	v_and_b32_e32 v73, 0xffff0000, v49
	s_waitcnt vmcnt(2)
	v_lshlrev_b32_e32 v66, 16, v50
	v_and_b32_e32 v67, 0xffff0000, v50
	v_lshlrev_b32_e32 v68, 16, v51
	v_and_b32_e32 v69, 0xffff0000, v51
	v_lshlrev_b32_e32 v62, 16, v52
	v_and_b32_e32 v63, 0xffff0000, v52
	v_lshlrev_b32_e32 v64, 16, v53
	v_and_b32_e32 v65, 0xffff0000, v53
	s_waitcnt vmcnt(1)
	v_lshlrev_b32_e32 v60, 16, v54
	v_and_b32_e32 v61, 0xffff0000, v54
	v_lshlrev_b32_e32 v58, 16, v55
	v_and_b32_e32 v59, 0xffff0000, v55
	v_lshlrev_b32_e32 v54, 16, v56
	v_and_b32_e32 v55, 0xffff0000, v56
	v_lshlrev_b32_e32 v56, 16, v57
	v_and_b32_e32 v57, 0xffff0000, v57
	s_waitcnt vmcnt(0)
	v_lshlrev_b32_e32 v50, 16, v78
	v_and_b32_e32 v51, 0xffff0000, v78
	v_lshlrev_b32_e32 v52, 16, v79
	v_and_b32_e32 v53, 0xffff0000, v79
	v_lshlrev_b32_e32 v48, 16, v80
	v_and_b32_e32 v49, 0xffff0000, v80
	v_lshlrev_b32_e32 v46, 16, v81
	v_and_b32_e32 v47, 0xffff0000, v81
	s_cbranch_scc1 .LBB0_612
	s_add_i32 s64, s36, 0xffffe001
	s_lshl_b64 s[12:13], s[64:65], 12
	v_lshl_add_u64 v[82:83], v[42:43], 0, s[12:13]
	v_mov_b32_e32 v78, v104
	v_mov_b32_e32 v79, v105
	v_mov_b32_e32 v80, v106
	v_mov_b32_e32 v81, v107
	v_lshlrev_b32_e32 v84, 16, v78
	v_and_b32_e32 v85, 0xffff0000, v78
	v_lshlrev_b32_e32 v78, 16, v79
	v_and_b32_e32 v79, 0xffff0000, v79
	v_pk_add_f32 v[76:77], v[76:77], v[78:79]
	v_lshlrev_b32_e32 v78, 16, v80
	v_and_b32_e32 v79, 0xffff0000, v80
	v_lshlrev_b32_e32 v80, 16, v81
	v_and_b32_e32 v81, 0xffff0000, v81
	v_pk_add_f32 v[72:73], v[72:73], v[80:81]
	v_pk_add_f32 v[70:71], v[70:71], v[78:79]
	v_mov_b32_e32 v78, v108
	v_mov_b32_e32 v79, v109
	v_mov_b32_e32 v80, v110
	v_mov_b32_e32 v81, v111
	v_pk_add_f32 v[74:75], v[74:75], v[84:85]
	v_lshlrev_b32_e32 v84, 16, v78
	v_and_b32_e32 v85, 0xffff0000, v78
	v_lshlrev_b32_e32 v78, 16, v79
	v_and_b32_e32 v79, 0xffff0000, v79
	v_pk_add_f32 v[68:69], v[68:69], v[78:79]
	v_lshlrev_b32_e32 v78, 16, v80
	v_and_b32_e32 v79, 0xffff0000, v80
	v_lshlrev_b32_e32 v80, 16, v81
	v_and_b32_e32 v81, 0xffff0000, v81
	v_pk_add_f32 v[64:65], v[64:65], v[80:81]
	v_pk_add_f32 v[62:63], v[62:63], v[78:79]
	v_mov_b32_e32 v78, v112
	v_mov_b32_e32 v79, v113
	v_mov_b32_e32 v80, v114
	v_mov_b32_e32 v81, v115
	v_pk_add_f32 v[66:67], v[66:67], v[84:85]
	v_lshlrev_b32_e32 v84, 16, v78
	v_and_b32_e32 v85, 0xffff0000, v78
	v_lshlrev_b32_e32 v78, 16, v79
	v_and_b32_e32 v79, 0xffff0000, v79
	v_pk_add_f32 v[58:59], v[58:59], v[78:79]
	v_lshlrev_b32_e32 v78, 16, v80
	v_and_b32_e32 v79, 0xffff0000, v80
	v_lshlrev_b32_e32 v80, 16, v81
	v_and_b32_e32 v81, 0xffff0000, v81
	v_pk_add_f32 v[56:57], v[56:57], v[80:81]
	v_pk_add_f32 v[54:55], v[54:55], v[78:79]
	v_mov_b32_e32 v78, v116
	v_mov_b32_e32 v79, v117
	v_mov_b32_e32 v80, v118
	v_mov_b32_e32 v81, v119
	v_pk_add_f32 v[60:61], v[60:61], v[84:85]
	v_lshlrev_b32_e32 v82, 16, v78
	v_and_b32_e32 v83, 0xffff0000, v78
	v_lshlrev_b32_e32 v78, 16, v79
	v_and_b32_e32 v79, 0xffff0000, v79
	v_pk_add_f32 v[52:53], v[52:53], v[78:79]
	v_lshlrev_b32_e32 v78, 16, v80
	v_and_b32_e32 v79, 0xffff0000, v80
	v_lshlrev_b32_e32 v80, 16, v81
	v_and_b32_e32 v81, 0xffff0000, v81
	v_pk_add_f32 v[50:51], v[50:51], v[82:83]
	v_pk_add_f32 v[46:47], v[46:47], v[80:81]
	v_pk_add_f32 v[48:49], v[48:49], v[78:79]
	s_branch .LBB0_612

.LBB0_688:
	v_lshrrev_b32_e32 v20, 1, v10
	v_and_b32_e32 v20, 24, v20
	v_and_b32_e32 v11, 15, v10
	v_lshlrev_b32_e32 v21, 1, v20
	v_lshlrev_b32_e32 v10, 2, v10
	s_lshl_b32 s13, s13, 5
	v_bfe_u32 v1, v0, 2, 4
	v_lshl_or_b32 v1, s16, 6, v1
	v_bfe_u32 v231, v0, 2, 4
	v_and_b32_e32 v230, 3, v0
	v_lshl_or_b32 v231, v230, 4, v231
	v_lshlrev_b32_e32 v231, 2, v231
	v_lshl_or_b32 v11, v11, 6, v21
	s_lshl_b32 s16, s16, 13
	v_and_b32_e32 v10, 32, v10
	s_and_b32 s13, s13, 0x60
	v_lshl_add_u64 v[12:13], s[90:91], 0, v[2:3]
	v_mov_b32_e32 v133, v3
	v_readlane_b32 s88, v252, 37
	v_bitop3_b32 v21, v11, s16, v10 bitop3:0xde
	s_lshl_b32 s16, s13, 7
	v_lshl_add_u64 v[14:15], s[90:91], 0, v[132:133]
	v_mov_b32_e32 v137, v3
	v_readlane_b32 s89, v252, 38
	v_bitop3_b32 v144, v11, s16, v10 bitop3:0xde
	s_add_i32 m0, s60, 0x18000
	v_lshl_add_u64 v[10:11], v[12:13], 0, s[66:67]
	v_lshl_add_u64 v[16:17], s[88:89], 0, v[136:137]
	v_mov_b32_e32 v135, v3
	global_load_lds_dwordx4 v[10:11], off
	v_lshl_add_u64 v[10:11], v[14:15], 0, s[66:67]
	s_add_i32 m0, s60, 0x1a000
	s_add_i32 s64, s60, 0x8000
	s_add_i32 s58, s60, 0xa000
	v_lshl_add_u64 v[18:19], s[88:89], 0, v[134:135]
	global_load_lds_dwordx4 v[10:11], off
	v_lshl_add_u64 v[10:11], v[16:17], 0, s[66:67]
	s_mov_b32 m0, s64
	s_add_u32 s16, s90, 0x80080
	global_load_lds_dwordx4 v[10:11], off
	v_lshl_add_u64 v[10:11], v[18:19], 0, s[66:67]
	s_mov_b32 m0, s58
	s_addc_u32 s17, s91, 0
	global_load_lds_dwordx4 v[10:11], off
	s_add_i32 m0, s60, 0x1c000
	v_lshl_add_u64 v[10:11], s[16:17], 0, v[2:3]
	global_load_lds_dwordx4 v[10:11], off
	v_lshl_add_u64 v[10:11], s[16:17], 0, v[132:133]
	s_add_i32 m0, s60, 0x1e000
	s_cmpk_lt_u32 s12, 0x100
	global_load_lds_dwordx4 v[10:11], off
	v_lshlrev_b32_e32 v10, 15, v8
	v_and_b32_e32 v10, 0xffff0000, v10
	v_lshl_add_u32 v7, v7, 12, v10
	v_and_b32_e32 v8, 1, v8
	v_lshl_or_b32 v7, v8, 6, v7
	v_lshl_add_u32 v138, v9, 1, v7
	v_lshlrev_b32_e32 v7, 15, v4
	v_and_b32_e32 v7, 0xffff0000, v7
	s_waitcnt vmcnt(8)
	s_barrier
	s_waitcnt vmcnt(6)
	v_lshl_add_u32 v5, v5, 12, v7
	v_and_b32_e32 v4, 1, v4
	v_lshl_or_b32 v4, v4, 6, v5
	v_readlane_b32 s16, v252, 33
	s_cselect_b64 s[68:69], -1, 0
	v_and_b32_e32 v145, 3, v0
	v_lshl_or_b32 v145, v145, 3, s13
	v_mov_b32_e32 v139, v3
	v_lshl_add_u32 v140, v6, 1, v4
	v_mov_b32_e32 v141, v3
	s_mov_b32 s59, 0
	v_add_u32_e32 v146, 0, v21
	v_readlane_b32 s12, v252, 32
	s_mov_b32 s13, s16
	s_barrier
	v_readlane_b32 s17, v252, 34
	s_branch .LBB0_691

.LBB0_755:
	v_readlane_b32 s84, v252, 20
	s_add_u32 s50, s86, 0x200080
	v_mov_b32_e32 v133, v3
	v_readlane_b32 s85, v252, 21
	s_addc_u32 s51, s87, 0
	s_add_i32 m0, s16, 0x18000
	v_lshl_add_u64 v[4:5], v[4:5], 0, s[66:67]
	v_lshl_add_u64 v[16:17], s[84:85], 0, v[132:133]
	v_mov_b32_e32 v135, v3
	global_load_lds_dwordx4 v[4:5], off
	v_lshl_add_u64 v[4:5], v[6:7], 0, s[66:67]
	s_add_i32 m0, s16, 0x1a000
	s_add_i32 s60, s16, 0x8000
	v_lshl_add_u64 v[18:19], s[84:85], 0, v[134:135]
	global_load_lds_dwordx4 v[4:5], off
	v_lshl_add_u64 v[4:5], v[16:17], 0, s[66:67]
	s_mov_b32 m0, s60
	s_add_i32 s61, s16, 0xa000
	global_load_lds_dwordx4 v[4:5], off
	v_lshl_add_u64 v[4:5], v[18:19], 0, s[66:67]
	s_mov_b32 m0, s61
	v_lshrrev_b32_e32 v20, 1, v14
	global_load_lds_dwordx4 v[4:5], off
	s_add_i32 m0, s16, 0x1c000
	v_lshl_add_u64 v[4:5], s[50:51], 0, v[2:3]
	global_load_lds_dwordx4 v[4:5], off
	v_lshl_add_u64 v[4:5], s[50:51], 0, v[136:137]
	s_add_i32 m0, s16, 0x1e000
	v_and_b32_e32 v20, 24, v20
	global_load_lds_dwordx4 v[4:5], off
	v_lshlrev_b32_e32 v4, 17, v8
	v_and_b32_e32 v4, 0xfffc0000, v4
	v_lshl_add_u32 v4, v9, 14, v4
	v_and_b32_e32 v5, 1, v8
	v_lshl_or_b32 v4, v5, 6, v4
	s_lshl_b32 s1, s1, 5
	v_lshl_add_u32 v138, v10, 1, v4
	v_lshlrev_b32_e32 v4, 17, v11
	v_and_b32_e32 v15, 15, v14
	v_lshlrev_b32_e32 v21, 1, v20
	v_lshlrev_b32_e32 v14, 2, v14
	s_and_b32 s1, s1, 0x60
	v_and_b32_e32 v4, 0xfffc0000, v4
	v_bfe_u32 v1, v0, 2, 4
	v_lshl_or_b32 v1, s23, 6, v1
	v_bfe_u32 v231, v0, 2, 4
	v_and_b32_e32 v230, 3, v0
	v_lshl_or_b32 v231, v230, 4, v231
	v_lshlrev_b32_e32 v231, 2, v231
	v_lshl_or_b32 v15, v15, 6, v21
	v_and_b32_e32 v14, 32, v14
	s_lshl_b32 s23, s23, 13
	s_lshl_b32 s29, s1, 7
	s_waitcnt vmcnt(8)
	s_barrier
	s_waitcnt vmcnt(6)
	v_lshl_add_u32 v4, v12, 14, v4
	v_and_b32_e32 v5, 1, v11
	v_bitop3_b32 v142, v15, s29, v14 bitop3:0xde
	v_bitop3_b32 v14, v15, s23, v14 bitop3:0xde
	s_cmpk_lt_u32 s0, 0x100
	v_and_b32_e32 v143, 3, v0
	v_lshl_or_b32 v143, v143, 3, s1
	v_lshl_or_b32 v4, v5, 6, v4
	v_readlane_b32 s0, v252, 17
	s_cselect_b64 s[68:69], -1, 0
	v_mov_b32_e32 v139, v3
	v_lshl_add_u32 v140, v13, 1, v4
	v_mov_b32_e32 v141, v3
	s_mov_b64 s[88:89], -1
	s_movk_i32 s51, 0x80
	s_mov_b32 s50, 0
	v_add_u32_e32 v144, 0, v14
	s_mov_b32 s54, s0
	s_barrier
	v_readlane_b32 s1, v252, 18
	s_branch .LBB0_758

.LBB0_855:
	v_and_b32_e32 v2, 63, v1
	s_ashr_i32 s12, s23, 5
	v_readlane_b32 s16, v252, 14
	s_and_b32 s12, s12, -2
	v_lshl_add_u32 v1, v2, 5, 0
	v_lshlrev_b32_e32 v2, 4, v2
	v_readlane_b32 s17, v252, 15
	v_lshl_add_u64 v[22:23], s[30:31], 0, v[2:3]
	v_lshl_add_u64 v[24:25], s[26:27], 0, v[2:3]
	v_add_co_u32_e32 v122, vcc, 0xfe000000, v24
	v_addc_co_u32_e32 v123, vcc, -1, v25, vcc
	v_lshl_add_u64 v[20:21], s[16:17], 0, v[2:3]
	v_lshl_add_u64 v[26:27], s[14:15], 0, v[2:3]
	s_add_i32 s23, s24, s12
	s_mov_b32 s29, 0
	s_waitcnt lgkmcnt(0)
	s_barrier
	s_branch .LBB0_857

.LBB0_857:
	s_add_i32 s36, s23, s29
	s_ashr_i32 s37, s36, 31
	s_lshl_b64 s[12:13], s[36:37], 12
	s_cmpk_lt_i32 s36, 0x2000
	s_cbranch_scc1 .Lmix2_p7a
	v_lshl_add_u64 v[120:121], v[122:123], 0, s[12:13]
	global_load_dwordx4 v[104:107], v[120:121], off
	global_load_dwordx4 v[108:111], v[120:121], off offset:1024
	global_load_dwordx4 v[112:115], v[120:121], off offset:2048
	global_load_dwordx4 v[116:119], v[120:121], off offset:3072
.Lmix2_p7a:
	v_lshl_add_u64 v[4:5], v[22:23], 0, s[12:13]
	v_lshl_add_u64 v[28:29], v[20:21], 0, s[12:13]
	global_load_dwordx4 v[30:33], v[4:5], off
	global_load_dwordx4 v[34:37], v[4:5], off offset:1024
	global_load_dwordx4 v[38:41], v[4:5], off offset:2048
	global_load_dwordx4 v[62:65], v[4:5], off offset:3072
	global_load_dwordx4 v[16:19], v[28:29], off
	global_load_dwordx4 v[12:15], v[28:29], off offset:1024
	global_load_dwordx4 v[8:11], v[28:29], off offset:2048
	s_nop 0
	global_load_dwordx4 v[4:7], v[28:29], off offset:3072
	s_cmpk_lt_i32 s36, 0x2000
	s_waitcnt vmcnt(7)
	v_lshlrev_b32_e32 v58, 16, v30
	v_and_b32_e32 v59, 0xffff0000, v30
	v_lshlrev_b32_e32 v60, 16, v31
	v_and_b32_e32 v61, 0xffff0000, v31
	v_lshlrev_b32_e32 v54, 16, v32
	v_and_b32_e32 v55, 0xffff0000, v32
	v_lshlrev_b32_e32 v56, 16, v33
	v_and_b32_e32 v57, 0xffff0000, v33
	s_waitcnt vmcnt(6)
	v_lshlrev_b32_e32 v50, 16, v34
	v_and_b32_e32 v51, 0xffff0000, v34
	v_lshlrev_b32_e32 v52, 16, v35
	v_and_b32_e32 v53, 0xffff0000, v35
	v_lshlrev_b32_e32 v46, 16, v36
	v_and_b32_e32 v47, 0xffff0000, v36
	v_lshlrev_b32_e32 v48, 16, v37
	v_and_b32_e32 v49, 0xffff0000, v37
	s_waitcnt vmcnt(5)
	v_lshlrev_b32_e32 v44, 16, v38
	v_and_b32_e32 v45, 0xffff0000, v38
	v_lshlrev_b32_e32 v42, 16, v39
	v_and_b32_e32 v43, 0xffff0000, v39
	v_lshlrev_b32_e32 v38, 16, v40
	v_and_b32_e32 v39, 0xffff0000, v40
	v_lshlrev_b32_e32 v40, 16, v41
	v_and_b32_e32 v41, 0xffff0000, v41
	s_waitcnt vmcnt(4)
	v_lshlrev_b32_e32 v34, 16, v62
	v_and_b32_e32 v35, 0xffff0000, v62
	v_lshlrev_b32_e32 v36, 16, v63
	v_and_b32_e32 v37, 0xffff0000, v63
	v_lshlrev_b32_e32 v32, 16, v64
	v_and_b32_e32 v33, 0xffff0000, v64
	v_lshlrev_b32_e32 v30, 16, v65
	v_and_b32_e32 v31, 0xffff0000, v65
	s_cbranch_scc1 .LBB0_859
	s_add_i32 s64, s36, 0xffffe000
	s_lshl_b64 s[12:13], s[64:65], 12
	v_lshl_add_u64 v[66:67], v[24:25], 0, s[12:13]
	v_mov_b32_e32 v62, v104
	v_mov_b32_e32 v63, v105
	v_mov_b32_e32 v64, v106
	v_mov_b32_e32 v65, v107
	v_lshlrev_b32_e32 v68, 16, v62
	v_and_b32_e32 v69, 0xffff0000, v62
	v_lshlrev_b32_e32 v62, 16, v63
	v_and_b32_e32 v63, 0xffff0000, v63
	v_pk_add_f32 v[60:61], v[60:61], v[62:63]
	v_lshlrev_b32_e32 v62, 16, v64
	v_and_b32_e32 v63, 0xffff0000, v64
	v_lshlrev_b32_e32 v64, 16, v65
	v_and_b32_e32 v65, 0xffff0000, v65
	v_pk_add_f32 v[56:57], v[56:57], v[64:65]
	v_pk_add_f32 v[54:55], v[54:55], v[62:63]
	v_mov_b32_e32 v62, v108
	v_mov_b32_e32 v63, v109
	v_mov_b32_e32 v64, v110
	v_mov_b32_e32 v65, v111
	v_pk_add_f32 v[58:59], v[58:59], v[68:69]
	v_lshlrev_b32_e32 v68, 16, v62
	v_and_b32_e32 v69, 0xffff0000, v62
	v_lshlrev_b32_e32 v62, 16, v63
	v_and_b32_e32 v63, 0xffff0000, v63
	v_pk_add_f32 v[52:53], v[52:53], v[62:63]
	v_lshlrev_b32_e32 v62, 16, v64
	v_and_b32_e32 v63, 0xffff0000, v64
	v_lshlrev_b32_e32 v64, 16, v65
	v_and_b32_e32 v65, 0xffff0000, v65
	v_pk_add_f32 v[48:49], v[48:49], v[64:65]
	v_pk_add_f32 v[46:47], v[46:47], v[62:63]
	v_mov_b32_e32 v62, v112
	v_mov_b32_e32 v63, v113
	v_mov_b32_e32 v64, v114
	v_mov_b32_e32 v65, v115
	v_pk_add_f32 v[50:51], v[50:51], v[68:69]
	v_lshlrev_b32_e32 v68, 16, v62
	v_and_b32_e32 v69, 0xffff0000, v62
	v_lshlrev_b32_e32 v62, 16, v63
	v_and_b32_e32 v63, 0xffff0000, v63
	v_pk_add_f32 v[42:43], v[42:43], v[62:63]
	v_lshlrev_b32_e32 v62, 16, v64
	v_and_b32_e32 v63, 0xffff0000, v64
	v_lshlrev_b32_e32 v64, 16, v65
	v_and_b32_e32 v65, 0xffff0000, v65
	v_pk_add_f32 v[40:41], v[40:41], v[64:65]
	v_pk_add_f32 v[38:39], v[38:39], v[62:63]
	v_mov_b32_e32 v62, v116
	v_mov_b32_e32 v63, v117
	v_mov_b32_e32 v64, v118
	v_mov_b32_e32 v65, v119
	v_pk_add_f32 v[44:45], v[44:45], v[68:69]
	v_lshlrev_b32_e32 v66, 16, v62
	v_and_b32_e32 v67, 0xffff0000, v62
	v_lshlrev_b32_e32 v62, 16, v63
	v_and_b32_e32 v63, 0xffff0000, v63
	v_pk_add_f32 v[36:37], v[36:37], v[62:63]
	v_lshlrev_b32_e32 v62, 16, v64
	v_and_b32_e32 v63, 0xffff0000, v64
	v_lshlrev_b32_e32 v64, 16, v65
	v_and_b32_e32 v65, 0xffff0000, v65
	v_pk_add_f32 v[34:35], v[34:35], v[66:67]
	v_pk_add_f32 v[30:31], v[30:31], v[64:65]
	v_pk_add_f32 v[32:33], v[32:33], v[62:63]
.LBB0_859:
	s_waitcnt vmcnt(0)
	v_lshlrev_b32_e32 v62, 16, v6
	v_and_b32_e32 v63, 0xffff0000, v6
	v_lshlrev_b32_e32 v64, 16, v7
	v_and_b32_e32 v65, 0xffff0000, v7
	v_mov_b32_e32 v6, v55
	v_mov_b32_e32 v7, v59
	v_lshlrev_b32_e32 v78, 16, v8
	v_and_b32_e32 v79, 0xffff0000, v8
	v_lshlrev_b32_e32 v80, 16, v9
	v_and_b32_e32 v81, 0xffff0000, v9
	v_lshlrev_b32_e32 v86, 16, v4
	v_and_b32_e32 v87, 0xffff0000, v4
	v_lshlrev_b32_e32 v88, 16, v5
	v_and_b32_e32 v89, 0xffff0000, v5
	v_mov_b32_e32 v4, v54
	v_mov_b32_e32 v5, v58
	v_pk_mul_f32 v[6:7], v[6:7], v[6:7]
	v_mov_b32_e32 v8, v57
	v_mov_b32_e32 v9, v61
	v_pk_fma_f32 v[4:5], v[4:5], v[4:5], v[6:7]
	v_mov_b32_e32 v6, v56
	v_mov_b32_e32 v7, v60
	v_pk_mul_f32 v[8:9], v[8:9], v[8:9]
	v_lshlrev_b32_e32 v82, 16, v10
	v_pk_fma_f32 v[6:7], v[6:7], v[6:7], v[8:9]
	v_pk_mul_f32 v[8:9], v[50:51], v[50:51]
	v_pk_add_f32 v[4:5], v[4:5], v[6:7]
	v_pk_mul_f32 v[6:7], v[52:53], v[52:53]
	v_and_b32_e32 v83, 0xffff0000, v10
	v_lshlrev_b32_e32 v84, 16, v11
	v_and_b32_e32 v85, 0xffff0000, v11
	v_pk_mov_b32 v[10:11], v[8:9], v[6:7] op_sel:[1,0]
	v_mov_b32_e32 v9, v7
	v_mul_f32_e32 v2, v46, v46
	v_pk_add_f32 v[6:7], v[10:11], v[8:9]
	v_pk_fma_f32 v[8:9], v[46:47], v[46:47], v[2:3] op_sel_hi:[1,1,0]
	v_mul_f32_e32 v2, v48, v48
	v_pk_add_f32 v[4:5], v[4:5], v[4:5] op_sel_hi:[0,1]
	v_pk_add_f32 v[6:7], v[6:7], v[6:7] op_sel_hi:[0,1]
	v_pk_fma_f32 v[10:11], v[48:49], v[48:49], v[2:3] op_sel_hi:[1,1,0]
	v_mul_f32_e32 v8, v44, v44
	v_mul_f32_e32 v10, v45, v45
	v_mul_f32_e32 v6, v42, v42
	v_mul_f32_e32 v4, v43, v43
	v_pk_add_f32 v[8:9], v[8:9], v[10:11]
	v_pk_add_f32 v[4:5], v[6:7], v[4:5]
	v_pk_mul_f32 v[6:7], v[40:41], v[40:41]
	v_pk_add_f32 v[4:5], v[8:9], v[4:5]
	v_pk_mul_f32 v[8:9], v[38:39], v[38:39]
	v_mul_f32_e32 v2, v34, v34
	v_pk_mov_b32 v[10:11], v[8:9], v[6:7] op_sel:[1,0]
	v_mov_b32_e32 v9, v7
	v_pk_add_f32 v[6:7], v[10:11], v[8:9]
	v_pk_fma_f32 v[8:9], v[34:35], v[34:35], v[2:3] op_sel_hi:[1,1,0]
	v_mul_f32_e32 v2, v36, v36
	v_pk_add_f32 v[4:5], v[4:5], v[4:5] op_sel_hi:[0,1]
	v_pk_add_f32 v[6:7], v[6:7], v[6:7] op_sel_hi:[0,1]
	v_pk_fma_f32 v[10:11], v[36:37], v[36:37], v[2:3] op_sel_hi:[1,1,0]
	v_mul_f32_e32 v8, v32, v32
	v_mul_f32_e32 v10, v33, v33
	v_mul_f32_e32 v6, v30, v30
	v_mul_f32_e32 v4, v31, v31
	v_pk_add_f32 v[8:9], v[8:9], v[10:11]
	v_pk_add_f32 v[4:5], v[6:7], v[4:5]
	s_lshl_b64 s[58:59], s[36:37], 11
	v_pk_add_f32 v[4:5], v[8:9], v[4:5]
	s_cmpk_lt_i32 s36, 0x2800
	v_add_f32_e32 v2, v4, v5
	v_mov_b32_e32 v4, v3
	s_cselect_b32 s12, 0x800, s41
	v_add_f32_dpp v2, v2, v2 quad_perm:[1,0,3,2] row_mask:0xf bank_mask:0xf bound_ctrl:1
	s_cmpk_gt_i32 s36, 0x1fff
	s_cselect_b32 s12, s12, 0
	v_add_f32_dpp v2, v2, v2 quad_perm:[2,3,0,1] row_mask:0xf bank_mask:0xf bound_ctrl:1
	s_lshl_b32 s12, s12, 2
	v_add_u32_e32 v90, s12, v1
	v_add_f32_dpp v2, v2, v2 row_ror:4 row_mask:0xf bank_mask:0xf bound_ctrl:1
	v_lshlrev_b32_e32 v66, 16, v16
	v_and_b32_e32 v67, 0xffff0000, v16
	v_add_f32_dpp v2, v2, v2 row_ror:8 row_mask:0xf bank_mask:0xf bound_ctrl:1
	v_lshlrev_b32_e32 v16, 16, v17
	v_and_b32_e32 v17, 0xffff0000, v17
	v_mov_b32_dpp v4, v2 row_bcast:15 row_mask:0xa bank_mask:0xf
	v_add_f32_e32 v2, v2, v4
	v_mov_b32_e32 v4, v3
	v_lshlrev_b32_e32 v70, 16, v12
	v_and_b32_e32 v71, 0xffff0000, v12
	v_mov_b32_dpp v4, v2 row_bcast:31 row_mask:0xc bank_mask:0xf
	v_add_f32_e32 v2, v2, v4
	ds_read_b128 v[4:7], v90
	ds_read_b128 v[8:11], v90 offset:16
	v_readlane_b32 s13, v2, 63
	v_lshlrev_b32_e32 v72, 16, v13
	v_and_b32_e32 v73, 0xffff0000, v13
	v_fma_f32 v2, s13, v245, v233
	v_rsq_f32_e32 v2, v2
	v_lshlrev_b32_e32 v74, 16, v14
	v_and_b32_e32 v75, 0xffff0000, v14
	v_lshlrev_b32_e32 v76, 16, v15
	v_and_b32_e32 v77, 0xffff0000, v15
	v_pk_mul_f32 v[14:15], v[2:3], v[58:59] op_sel_hi:[0,1]
	v_pk_mul_f32 v[12:13], v[2:3], v[60:61] op_sel_hi:[0,1]
	v_lshlrev_b32_e32 v68, 16, v18
	v_and_b32_e32 v69, 0xffff0000, v18
	v_lshlrev_b32_e32 v18, 16, v19
	v_and_b32_e32 v19, 0xffff0000, v19
	s_waitcnt lgkmcnt(1)
	v_pk_fma_f32 v[12:13], v[6:7], v[12:13], v[16:17]
	v_pk_fma_f32 v[16:17], v[4:5], v[14:15], v[66:67]
	v_pk_mul_f32 v[4:5], v[2:3], v[54:55] op_sel_hi:[0,1]
	v_pk_mul_f32 v[6:7], v[2:3], v[56:57] op_sel_hi:[0,1]
	s_waitcnt lgkmcnt(0)
	v_pk_fma_f32 v[14:15], v[10:11], v[6:7], v[18:19]
	v_pk_fma_f32 v[18:19], v[8:9], v[4:5], v[68:69]
	ds_read_b128 v[6:9], v90 offset:2048
	v_pk_mul_f32 v[10:11], v[2:3], v[50:51] op_sel_hi:[0,1]
	v_pk_mul_f32 v[4:5], v[2:3], v[52:53] op_sel_hi:[0,1]
	v_pk_mul_f32 v[50:51], v[2:3], v[46:47] op_sel_hi:[0,1]
	v_pk_mul_f32 v[46:47], v[2:3], v[48:49] op_sel_hi:[0,1]
	s_waitcnt lgkmcnt(0)
	v_pk_fma_f32 v[4:5], v[8:9], v[4:5], v[72:73]
	v_pk_fma_f32 v[6:7], v[6:7], v[10:11], v[70:71]
	ds_read_b128 v[8:11], v90 offset:2064
	v_pk_mul_f32 v[32:33], v[2:3], v[32:33] op_sel_hi:[0,1]
	v_pk_mul_f32 v[30:31], v[2:3], v[30:31] op_sel_hi:[0,1]
	s_waitcnt lgkmcnt(0)
	v_pk_fma_f32 v[48:49], v[8:9], v[50:51], v[74:75]
	ds_read_b128 v[50:53], v90 offset:4096
	v_pk_fma_f32 v[46:47], v[10:11], v[46:47], v[76:77]
	v_pk_mul_f32 v[10:11], v[2:3], v[44:45] op_sel_hi:[0,1]
	v_pk_mul_f32 v[8:9], v[2:3], v[42:43] op_sel_hi:[0,1]
	ds_read_b128 v[42:45], v90 offset:4112
	s_waitcnt lgkmcnt(1)
	v_pk_fma_f32 v[10:11], v[50:51], v[10:11], v[78:79]
	v_pk_mul_f32 v[50:51], v[2:3], v[38:39] op_sel_hi:[0,1]
	v_pk_mul_f32 v[38:39], v[2:3], v[40:41] op_sel_hi:[0,1]
	v_pk_fma_f32 v[8:9], v[52:53], v[8:9], v[80:81]
	s_waitcnt lgkmcnt(0)
	v_pk_fma_f32 v[38:39], v[44:45], v[38:39], v[84:85]
	v_pk_fma_f32 v[40:41], v[42:43], v[50:51], v[82:83]
	ds_read_b128 v[42:45], v90 offset:6144
	v_pk_mul_f32 v[50:51], v[2:3], v[34:35] op_sel_hi:[0,1]
	v_pk_mul_f32 v[34:35], v[2:3], v[36:37] op_sel_hi:[0,1]
	v_mul_f32_e32 v2, v48, v48
	s_waitcnt lgkmcnt(0)
	v_pk_fma_f32 v[34:35], v[34:35], v[44:45], v[88:89]
	v_pk_fma_f32 v[36:37], v[50:51], v[42:43], v[86:87]
	ds_read_b128 v[42:45], v90 offset:6160
	s_waitcnt lgkmcnt(0)
	v_pk_fma_f32 v[30:31], v[30:31], v[44:45], v[64:65]
	v_pk_fma_f32 v[32:33], v[32:33], v[42:43], v[62:63]
	v_cvt_pk_bf16_f32 v42, v16, v17
	v_cvt_pk_bf16_f32 v43, v12, v13
	v_cvt_pk_bf16_f32 v44, v18, v19
	v_cvt_pk_bf16_f32 v45, v14, v15
	global_store_dwordx4 v[28:29], v[42:45], off
	s_nop 1
	v_cvt_pk_bf16_f32 v42, v6, v7
	v_cvt_pk_bf16_f32 v43, v4, v5
	v_cvt_pk_bf16_f32 v44, v48, v49
	v_cvt_pk_bf16_f32 v45, v46, v47
	global_store_dwordx4 v[28:29], v[42:45], off offset:1024
	s_nop 1
	v_cvt_pk_bf16_f32 v42, v10, v11
	v_cvt_pk_bf16_f32 v43, v8, v9
	v_cvt_pk_bf16_f32 v44, v40, v41
	v_cvt_pk_bf16_f32 v45, v38, v39
	global_store_dwordx4 v[28:29], v[42:45], off offset:2048
	s_nop 1
	v_cvt_pk_bf16_f32 v42, v36, v37
	v_cvt_pk_bf16_f32 v43, v34, v35
	v_cvt_pk_bf16_f32 v44, v32, v33
	v_cvt_pk_bf16_f32 v45, v30, v31
	global_store_dwordx4 v[28:29], v[42:45], off offset:3072
	v_mov_b32_e32 v28, v16
	v_mov_b32_e32 v29, v18
	v_mov_b32_e32 v42, v17
	v_mov_b32_e32 v43, v19
	v_pk_mul_f32 v[42:43], v[42:43], v[42:43]
	v_mov_b32_e32 v44, v13
	v_mov_b32_e32 v45, v15
	v_pk_fma_f32 v[28:29], v[28:29], v[28:29], v[42:43]
	v_mov_b32_e32 v42, v12
	v_mov_b32_e32 v43, v14
	v_pk_mul_f32 v[44:45], v[44:45], v[44:45]
	s_nop 0
	v_pk_fma_f32 v[42:43], v[42:43], v[42:43], v[44:45]
	v_pk_mul_f32 v[44:45], v[6:7], v[6:7]
	v_pk_add_f32 v[28:29], v[28:29], v[42:43]
	v_pk_mul_f32 v[42:43], v[4:5], v[4:5]
	v_pk_add_f32 v[28:29], v[28:29], v[28:29] op_sel_hi:[0,1]
	v_pk_mov_b32 v[50:51], v[44:45], v[42:43] op_sel:[1,0]
	v_mov_b32_e32 v45, v43
	v_pk_add_f32 v[42:43], v[50:51], v[44:45]
	v_pk_fma_f32 v[44:45], v[48:49], v[48:49], v[2:3] op_sel_hi:[1,1,0]
	v_mul_f32_e32 v2, v46, v46
	v_pk_add_f32 v[42:43], v[42:43], v[42:43] op_sel_hi:[0,1]
	v_pk_fma_f32 v[50:51], v[46:47], v[46:47], v[2:3] op_sel_hi:[1,1,0]
	v_mul_f32_e32 v44, v10, v10
	v_mul_f32_e32 v50, v11, v11
	v_mul_f32_e32 v42, v8, v8
	v_mul_f32_e32 v28, v9, v9
	v_pk_add_f32 v[44:45], v[44:45], v[50:51]
	v_pk_add_f32 v[28:29], v[42:43], v[28:29]
	v_pk_mul_f32 v[42:43], v[38:39], v[38:39]
	v_pk_add_f32 v[28:29], v[44:45], v[28:29]
	v_pk_mul_f32 v[44:45], v[40:41], v[40:41]
	v_mul_f32_e32 v2, v36, v36
	v_pk_mov_b32 v[50:51], v[44:45], v[42:43] op_sel:[1,0]
	v_mov_b32_e32 v45, v43
	v_pk_add_f32 v[42:43], v[50:51], v[44:45]
	v_pk_fma_f32 v[44:45], v[36:37], v[36:37], v[2:3] op_sel_hi:[1,1,0]
	v_mul_f32_e32 v2, v34, v34
	v_pk_add_f32 v[28:29], v[28:29], v[28:29] op_sel_hi:[0,1]
	v_pk_add_f32 v[42:43], v[42:43], v[42:43] op_sel_hi:[0,1]
	v_pk_fma_f32 v[50:51], v[34:35], v[34:35], v[2:3] op_sel_hi:[1,1,0]
	v_mul_f32_e32 v44, v32, v32
	v_mul_f32_e32 v50, v33, v33
	v_mul_f32_e32 v42, v30, v30
	v_mul_f32_e32 v28, v31, v31
	v_pk_add_f32 v[44:45], v[44:45], v[50:51]
	v_pk_add_f32 v[28:29], v[42:43], v[28:29]
	s_nop 0
	v_pk_add_f32 v[28:29], v[44:45], v[28:29]
	ds_read_b128 v[42:45], v90 offset:24576
	ds_read_b128 v[50:53], v90 offset:24592
	ds_read_b128 v[54:57], v90 offset:49152
	ds_read_b128 v[58:61], v90 offset:49168
	v_add_f32_e32 v2, v28, v29
	v_mov_b32_e32 v28, v3
	s_nop 0
	v_add_f32_dpp v2, v2, v2 quad_perm:[1,0,3,2] row_mask:0xf bank_mask:0xf bound_ctrl:1
	s_nop 1
	v_add_f32_dpp v2, v2, v2 quad_perm:[2,3,0,1] row_mask:0xf bank_mask:0xf bound_ctrl:1
	s_nop 1
	v_add_f32_dpp v2, v2, v2 row_ror:4 row_mask:0xf bank_mask:0xf bound_ctrl:1
	s_nop 1
	v_add_f32_dpp v2, v2, v2 row_ror:8 row_mask:0xf bank_mask:0xf bound_ctrl:1
	s_nop 1
	v_mov_b32_dpp v28, v2 row_bcast:15 row_mask:0xa bank_mask:0xf
	v_add_f32_e32 v2, v2, v28
	v_mov_b32_e32 v28, v3
	s_nop 1
	v_mov_b32_dpp v28, v2 row_bcast:31 row_mask:0xc bank_mask:0xf
	v_add_f32_e32 v2, v2, v28
	s_nop 0
	v_readlane_b32 s12, v2, 63
	s_nop 1
	v_fma_f32 v2, s12, v245, v233
	v_rsq_f32_e32 v2, v2
	s_nop 0
	v_pk_mul_f32 v[16:17], v[16:17], v[2:3] op_sel_hi:[1,0]
	v_pk_mul_f32 v[12:13], v[12:13], v[2:3] op_sel_hi:[1,0]
	v_pk_mul_f32 v[14:15], v[14:15], v[2:3] op_sel_hi:[1,0]
	s_waitcnt lgkmcnt(1)
	v_pk_fma_f32 v[28:29], v[44:45], v[12:13], v[56:57]
	v_pk_fma_f32 v[12:13], v[42:43], v[16:17], v[54:55]
	v_pk_mul_f32 v[16:17], v[18:19], v[2:3] op_sel_hi:[1,0]
	s_waitcnt lgkmcnt(0)
	v_pk_fma_f32 v[18:19], v[52:53], v[14:15], v[60:61]
	v_pk_fma_f32 v[14:15], v[50:51], v[16:17], v[58:59]
	v_cvt_pk_bf16_f32 v12, v12, v13
	v_cvt_pk_bf16_f32 v13, v28, v29
	v_cvt_pk_bf16_f32 v14, v14, v15
	v_cvt_pk_bf16_f32 v15, v18, v19
	v_lshl_add_u64 v[28:29], s[58:59], 1, v[26:27]
	global_store_dwordx4 v[28:29], v[12:15], off
	ds_read_b128 v[12:15], v90 offset:26624
	ds_read_b128 v[16:19], v90 offset:26640
	ds_read_b128 v[42:45], v90 offset:51200
	ds_read_b128 v[50:53], v90 offset:51216
	v_pk_mul_f32 v[6:7], v[6:7], v[2:3] op_sel_hi:[1,0]
	v_pk_mul_f32 v[4:5], v[4:5], v[2:3] op_sel_hi:[1,0]
	v_pk_mul_f32 v[10:11], v[10:11], v[2:3] op_sel_hi:[1,0]
	s_waitcnt lgkmcnt(1)
	v_pk_fma_f32 v[14:15], v[4:5], v[14:15], v[44:45]
	v_pk_fma_f32 v[4:5], v[6:7], v[12:13], v[42:43]
	v_pk_mul_f32 v[6:7], v[48:49], v[2:3] op_sel_hi:[1,0]
	v_pk_mul_f32 v[12:13], v[46:47], v[2:3] op_sel_hi:[1,0]
	s_waitcnt lgkmcnt(0)
	v_pk_fma_f32 v[6:7], v[6:7], v[16:17], v[50:51]
	v_pk_fma_f32 v[12:13], v[12:13], v[18:19], v[52:53]
	v_cvt_pk_bf16_f32 v4, v4, v5
	v_cvt_pk_bf16_f32 v5, v14, v15
	v_cvt_pk_bf16_f32 v6, v6, v7
	v_cvt_pk_bf16_f32 v7, v12, v13
	global_store_dwordx4 v[28:29], v[4:7], off offset:1024
	ds_read_b128 v[4:7], v90 offset:28672
	ds_read_b128 v[12:15], v90 offset:28688
	ds_read_b128 v[16:19], v90 offset:53248
	ds_read_b128 v[42:45], v90 offset:53264
	v_pk_mul_f32 v[8:9], v[8:9], v[2:3] op_sel_hi:[1,0]
	v_pk_mul_f32 v[36:37], v[36:37], v[2:3] op_sel_hi:[1,0]
	v_pk_mul_f32 v[34:35], v[34:35], v[2:3] op_sel_hi:[1,0]
	s_waitcnt lgkmcnt(1)
	v_pk_fma_f32 v[6:7], v[8:9], v[6:7], v[18:19]
	v_pk_fma_f32 v[4:5], v[10:11], v[4:5], v[16:17]
	v_pk_mul_f32 v[8:9], v[40:41], v[2:3] op_sel_hi:[1,0]
	v_pk_mul_f32 v[10:11], v[38:39], v[2:3] op_sel_hi:[1,0]
	s_waitcnt lgkmcnt(0)
	v_pk_fma_f32 v[8:9], v[8:9], v[12:13], v[42:43]
	v_pk_fma_f32 v[10:11], v[10:11], v[14:15], v[44:45]
	v_cvt_pk_bf16_f32 v4, v4, v5
	v_cvt_pk_bf16_f32 v5, v6, v7
	v_cvt_pk_bf16_f32 v6, v8, v9
	v_cvt_pk_bf16_f32 v7, v10, v11
	global_store_dwordx4 v[28:29], v[4:7], off offset:2048
	ds_read_b128 v[4:7], v90 offset:30720
	ds_read_b128 v[8:11], v90 offset:30736
	ds_read_b128 v[12:15], v90 offset:55296
	ds_read_b128 v[16:19], v90 offset:55312
	s_add_i32 s58, s36, 1
	s_ashr_i32 s59, s58, 31
	s_lshl_b64 s[12:13], s[58:59], 12
	s_waitcnt lgkmcnt(1)
	v_pk_fma_f32 v[6:7], v[34:35], v[6:7], v[14:15]
	v_pk_fma_f32 v[4:5], v[36:37], v[4:5], v[12:13]
	v_pk_mul_f32 v[12:13], v[32:33], v[2:3] op_sel_hi:[1,0]
	v_pk_mul_f32 v[14:15], v[30:31], v[2:3] op_sel_hi:[1,0]
	s_waitcnt lgkmcnt(0)
	v_pk_fma_f32 v[8:9], v[12:13], v[8:9], v[16:17]
	v_pk_fma_f32 v[10:11], v[14:15], v[10:11], v[18:19]
	v_cvt_pk_bf16_f32 v4, v4, v5
	v_cvt_pk_bf16_f32 v5, v6, v7
	v_cvt_pk_bf16_f32 v6, v8, v9
	v_cvt_pk_bf16_f32 v7, v10, v11
	global_store_dwordx4 v[28:29], v[4:7], off offset:3072
	s_cmpk_lt_i32 s36, 0x1fff
	s_cbranch_scc1 .Lmix2_p7b
	v_lshl_add_u64 v[120:121], v[122:123], 0, s[12:13]
	global_load_dwordx4 v[104:107], v[120:121], off
	global_load_dwordx4 v[108:111], v[120:121], off offset:1024
	global_load_dwordx4 v[112:115], v[120:121], off offset:2048
	global_load_dwordx4 v[116:119], v[120:121], off offset:3072
.Lmix2_p7b:
	v_lshl_add_u64 v[28:29], v[20:21], 0, s[12:13]
	global_load_dwordx4 v[16:19], v[28:29], off
	global_load_dwordx4 v[12:15], v[28:29], off offset:1024
	global_load_dwordx4 v[8:11], v[28:29], off offset:2048
	global_load_dwordx4 v[4:7], v[28:29], off offset:3072
	v_lshl_add_u64 v[54:55], v[22:23], 0, s[12:13]
	global_load_dwordx4 v[30:33], v[54:55], off
	global_load_dwordx4 v[38:41], v[54:55], off offset:1024
	global_load_dwordx4 v[46:49], v[54:55], off offset:2048
	global_load_dwordx4 v[60:63], v[54:55], off offset:3072
	s_cmpk_lt_i32 s36, 0x1fff
	s_waitcnt vmcnt(3)
	v_lshlrev_b32_e32 v34, 16, v30
	v_and_b32_e32 v35, 0xffff0000, v30
	v_lshlrev_b32_e32 v36, 16, v31
	v_and_b32_e32 v37, 0xffff0000, v31
	v_lshlrev_b32_e32 v30, 16, v32
	v_and_b32_e32 v31, 0xffff0000, v32
	v_lshlrev_b32_e32 v32, 16, v33
	v_and_b32_e32 v33, 0xffff0000, v33
	s_waitcnt vmcnt(2)
	v_lshlrev_b32_e32 v42, 16, v38
	v_and_b32_e32 v43, 0xffff0000, v38
	v_lshlrev_b32_e32 v44, 16, v39
	v_and_b32_e32 v45, 0xffff0000, v39
	v_lshlrev_b32_e32 v38, 16, v40
	v_and_b32_e32 v39, 0xffff0000, v40
	v_lshlrev_b32_e32 v40, 16, v41
	v_and_b32_e32 v41, 0xffff0000, v41
	s_waitcnt vmcnt(1)
	v_lshlrev_b32_e32 v52, 16, v46
	v_and_b32_e32 v53, 0xffff0000, v46
	v_lshlrev_b32_e32 v50, 16, v47
	v_and_b32_e32 v51, 0xffff0000, v47
	v_lshlrev_b32_e32 v46, 16, v48
	v_and_b32_e32 v47, 0xffff0000, v48
	v_lshlrev_b32_e32 v48, 16, v49
	v_and_b32_e32 v49, 0xffff0000, v49
	s_waitcnt vmcnt(0)
	v_lshlrev_b32_e32 v58, 16, v60
	v_and_b32_e32 v59, 0xffff0000, v60
	v_lshlrev_b32_e32 v60, 16, v61
	v_and_b32_e32 v61, 0xffff0000, v61
	v_lshlrev_b32_e32 v56, 16, v62
	v_and_b32_e32 v57, 0xffff0000, v62
	v_lshlrev_b32_e32 v54, 16, v63
	v_and_b32_e32 v55, 0xffff0000, v63
	s_cbranch_scc1 .LBB0_856
	s_add_i32 s64, s36, 0xffffe001
	s_lshl_b64 s[12:13], s[64:65], 12
	v_lshl_add_u64 v[66:67], v[24:25], 0, s[12:13]
	v_mov_b32_e32 v62, v104
	v_mov_b32_e32 v63, v105
	v_mov_b32_e32 v64, v106
	v_mov_b32_e32 v65, v107
	v_lshlrev_b32_e32 v68, 16, v62
	v_and_b32_e32 v69, 0xffff0000, v62
	v_lshlrev_b32_e32 v62, 16, v63
	v_and_b32_e32 v63, 0xffff0000, v63
	v_pk_add_f32 v[36:37], v[36:37], v[62:63]
	v_lshlrev_b32_e32 v62, 16, v64
	v_and_b32_e32 v63, 0xffff0000, v64
	v_lshlrev_b32_e32 v64, 16, v65
	v_and_b32_e32 v65, 0xffff0000, v65
	v_pk_add_f32 v[32:33], v[32:33], v[64:65]
	v_pk_add_f32 v[30:31], v[30:31], v[62:63]
	v_mov_b32_e32 v62, v108
	v_mov_b32_e32 v63, v109
	v_mov_b32_e32 v64, v110
	v_mov_b32_e32 v65, v111
	v_pk_add_f32 v[34:35], v[34:35], v[68:69]
	v_lshlrev_b32_e32 v68, 16, v62
	v_and_b32_e32 v69, 0xffff0000, v62
	v_lshlrev_b32_e32 v62, 16, v63
	v_and_b32_e32 v63, 0xffff0000, v63
	v_pk_add_f32 v[44:45], v[44:45], v[62:63]
	v_lshlrev_b32_e32 v62, 16, v64
	v_and_b32_e32 v63, 0xffff0000, v64
	v_lshlrev_b32_e32 v64, 16, v65
	v_and_b32_e32 v65, 0xffff0000, v65
	v_pk_add_f32 v[40:41], v[40:41], v[64:65]
	v_pk_add_f32 v[38:39], v[38:39], v[62:63]
	v_mov_b32_e32 v62, v112
	v_mov_b32_e32 v63, v113
	v_mov_b32_e32 v64, v114
	v_mov_b32_e32 v65, v115
	v_pk_add_f32 v[42:43], v[42:43], v[68:69]
	v_lshlrev_b32_e32 v68, 16, v62
	v_and_b32_e32 v69, 0xffff0000, v62
	v_lshlrev_b32_e32 v62, 16, v63
	v_and_b32_e32 v63, 0xffff0000, v63
	v_pk_add_f32 v[50:51], v[50:51], v[62:63]
	v_lshlrev_b32_e32 v62, 16, v64
	v_and_b32_e32 v63, 0xffff0000, v64
	v_lshlrev_b32_e32 v64, 16, v65
	v_and_b32_e32 v65, 0xffff0000, v65
	v_pk_add_f32 v[48:49], v[48:49], v[64:65]
	v_pk_add_f32 v[46:47], v[46:47], v[62:63]
	v_mov_b32_e32 v62, v116
	v_mov_b32_e32 v63, v117
	v_mov_b32_e32 v64, v118
	v_mov_b32_e32 v65, v119
	v_pk_add_f32 v[52:53], v[52:53], v[68:69]
	v_lshlrev_b32_e32 v66, 16, v62
	v_and_b32_e32 v67, 0xffff0000, v62
	v_lshlrev_b32_e32 v62, 16, v63
	v_and_b32_e32 v63, 0xffff0000, v63
	v_pk_add_f32 v[60:61], v[60:61], v[62:63]
	v_lshlrev_b32_e32 v62, 16, v64
	v_and_b32_e32 v63, 0xffff0000, v64
	v_lshlrev_b32_e32 v64, 16, v65
	v_and_b32_e32 v65, 0xffff0000, v65
	v_pk_add_f32 v[58:59], v[58:59], v[66:67]
	v_pk_add_f32 v[54:55], v[54:55], v[64:65]
	v_pk_add_f32 v[56:57], v[56:57], v[62:63]
	s_branch .LBB0_856
